# diff-attention tile loops: K fragments read three MFMAs ahead through a third buffer (v214-217), V fragment buffers rotated so the first two operands' transposed reads issue right after the last QK MF
# speedup vs baseline: 1.0117x; 1.0117x over previous
.LBB0_291:
	v_add_u32_e32 v0, s2, v199
	ds_read_b128 v[130:133], v0
	s_add_i32 s0, s47, -2
	ds_read_b128 v[188:191], v0 offset:1024
	ds_read_b128 v[248:251], v0 offset:2048
	ds_read_b128 v[214:217], v0 offset:3072
	s_waitcnt lgkmcnt(3)
	v_mfma_f32_32x32x16_bf16 v[130:145], v[130:133], v[146:149], 0
	s_waitcnt lgkmcnt(2)
	v_mfma_f32_32x32x16_bf16 v[130:145], v[188:191], v[150:153], v[130:145]
	ds_read_b128 v[188:191], v0 offset:4096
	s_cmp_lt_u32 s47, s44
	s_cbranch_scc0 .Lmy_a_nok1
	s_mov_b32 m0, s52
	s_nop 0
	global_load_lds_dwordx4 v[210:211], off
.Lmy_a_nok1:
	s_waitcnt lgkmcnt(2)
	v_mfma_f32_32x32x16_bf16 v[130:145], v[248:251], v[154:157], v[130:145]
	ds_read_b128 v[248:251], v0 offset:5120
	s_waitcnt lgkmcnt(2)
	v_mfma_f32_32x32x16_bf16 v[130:145], v[214:217], v[158:161], v[130:145]
	ds_read_b128 v[214:217], v0 offset:6144
	s_waitcnt lgkmcnt(2)
	v_mfma_f32_32x32x16_bf16 v[130:145], v[188:191], v[162:165], v[130:145]
	ds_read_b128 v[188:191], v0 offset:7168
	s_cmp_lt_u32 s47, s44
	s_cbranch_scc0 .Lmy_a_nok2
	s_mov_b32 m0, s53
	s_nop 0
	global_load_lds_dwordx4 v[208:209], off
.Lmy_a_nok2:
	s_waitcnt lgkmcnt(2)
	v_mfma_f32_32x32x16_bf16 v[130:145], v[248:251], v[166:169], v[130:145]
	s_waitcnt lgkmcnt(1)
	v_mfma_f32_32x32x16_bf16 v[130:145], v[214:217], v[170:173], v[130:145]
	s_waitcnt lgkmcnt(0)
	v_mfma_f32_32x32x16_bf16 v[130:145], v[188:191], v[174:177], v[130:145]
	s_lshl_b32 s3, s49, 14
	v_add_u32_e32 v252, s3, v224
	v_add_u32_e32 v253, s3, v228
	ds_read_b64_tr_b16 v[190:191], v252 offset:49152
	ds_read_b64_tr_b16 v[192:193], v252 offset:53248
	ds_read_b64_tr_b16 v[248:249], v253 offset:49152
	ds_read_b64_tr_b16 v[250:251], v253 offset:53248
	s_cmp_lt_u32 s0, s43
	s_cbranch_scc1 .LBB0_293
	v_add_u32_e32 v0, s46, v223
	v_add_u32_e32 v187, 32, v0
	v_cmp_lt_u32_e32 vcc, v187, v201
	s_nop 1
	v_cndmask_b32_e32 v131, v246, v131, vcc
	v_cmp_le_u32_e32 vcc, v187, v201
	v_add_u32_e32 v187, 34, v0
	s_nop 0
	v_cndmask_b32_e32 v130, v246, v130, vcc
	v_cmp_le_u32_e32 vcc, v187, v201
	v_add_u32_e32 v187, 35, v0
	s_nop 0
	v_cndmask_b32_e32 v132, v246, v132, vcc
	v_cmp_le_u32_e32 vcc, v187, v201
	v_add_u32_e32 v187, 40, v0
	s_nop 0
	v_cndmask_b32_e32 v133, v246, v133, vcc
	v_cmp_le_u32_e32 vcc, v187, v201
	v_add_u32_e32 v187, 41, v0
	s_nop 0
	v_cndmask_b32_e32 v134, v246, v134, vcc
	v_cmp_le_u32_e32 vcc, v187, v201
	v_add_u32_e32 v187, 42, v0
	s_nop 0
	v_cndmask_b32_e32 v135, v246, v135, vcc
	v_cmp_le_u32_e32 vcc, v187, v201
	v_add_u32_e32 v187, 43, v0
	s_nop 0
	v_cndmask_b32_e32 v136, v246, v136, vcc
	v_cmp_le_u32_e32 vcc, v187, v201
	v_add_u32_e32 v187, 48, v0
	s_nop 0
	v_cndmask_b32_e32 v137, v246, v137, vcc
	v_cmp_le_u32_e32 vcc, v187, v201
	v_add_u32_e32 v187, 49, v0
	s_nop 0
	v_cndmask_b32_e32 v138, v246, v138, vcc
	v_cmp_le_u32_e32 vcc, v187, v201
	v_add_u32_e32 v187, 50, v0
	s_nop 0
	v_cndmask_b32_e32 v139, v246, v139, vcc
	v_cmp_le_u32_e32 vcc, v187, v201
	v_add_u32_e32 v187, 51, v0
	s_nop 0
	v_cndmask_b32_e32 v140, v246, v140, vcc
	v_cmp_le_u32_e32 vcc, v187, v201
	v_add_u32_e32 v187, 56, v0
	s_nop 0
	v_cndmask_b32_e32 v141, v246, v141, vcc
	v_cmp_le_u32_e32 vcc, v187, v201
	v_add_u32_e32 v187, 57, v0
	s_nop 0
	v_cndmask_b32_e32 v142, v246, v142, vcc
	v_cmp_le_u32_e32 vcc, v187, v201
	v_add_u32_e32 v187, 58, v0
	v_add_u32_e32 v0, 59, v0
	v_cndmask_b32_e32 v143, v246, v143, vcc
	v_cmp_le_u32_e32 vcc, v187, v201
	s_nop 1
	v_cndmask_b32_e32 v144, v246, v144, vcc
	v_cmp_le_u32_e32 vcc, v0, v201
	s_nop 1
	v_cndmask_b32_e32 v145, v246, v145, vcc
.LBB0_293:
	s_nop 2
	v_max3_f32 v0, v130, v131, v132
	v_max3_f32 v187, v133, v134, v135
	v_max3_f32 v188, v136, v137, v138
	v_max3_f32 v189, v139, v140, v141
	v_max3_f32 v0, v0, v142, v143
	v_max3_f32 v187, v187, v144, v145
	v_max3_f32 v0, v0, v187, v188
	v_max_f32_e32 v0, v0, v189
	v_mov_b32_e32 v187, v0
	s_nop 1
	v_permlane32_swap_b32_e32 v0, v187
	v_max_f32_e32 v0, v0, v187
	v_add_f32_e32 v187, 0x41000000, v186
	v_cmp_gt_f32_e32 vcc, v0, v187
	s_cmp_eq_u64 vcc, 0
	v_max_f32_e32 v0, v186, v0
	s_cselect_b64 s[0:1], -1, 0
	v_cndmask_b32_e64 v0, v0, v186, s[0:1]
	v_sub_f32_e32 v247, v186, v0
	v_exp_f32_e32 v247, v247
	v_add_u32_e32 v254, s3, v229
	ds_read_b64_tr_b16 v[186:187], v254 offset:49152
	ds_read_b64_tr_b16 v[188:189], v254 offset:53248
	s_waitcnt lgkmcnt(4)
	v_mfma_f32_32x32x16_bf16 v[114:129], v[182:185], v[190:193], v[114:129]
	v_add_u32_e32 v195, s3, v230
	ds_read_b64_tr_b16 v[190:191], v195 offset:49152
	ds_read_b64_tr_b16 v[192:193], v195 offset:53248
	v_sub_f32_e32 v130, v130, v0
	v_exp_f32_e32 v1, v130
	s_waitcnt lgkmcnt(4)
	v_mfma_f32_32x32x16_bf16 v[98:113], v[182:185], v[248:251], v[98:113]
	ds_read_b64_tr_b16 v[248:249], v252 offset:49408
	ds_read_b64_tr_b16 v[250:251], v252 offset:53504
	v_sub_f32_e32 v131, v131, v0
	v_exp_f32_e32 v131, v131
	v_add_f32_e32 v130, 0, v1
	s_waitcnt lgkmcnt(4)
	v_mfma_f32_32x32x16_bf16 v[82:97], v[182:185], v[186:189], v[82:97]
	ds_read_b64_tr_b16 v[186:187], v253 offset:49408
	ds_read_b64_tr_b16 v[188:189], v253 offset:53504
	v_sub_f32_e32 v132, v132, v0
	v_exp_f32_e32 v132, v132
	v_add_f32_e32 v130, v131, v130
	s_waitcnt lgkmcnt(4)
	v_mfma_f32_32x32x16_bf16 v[66:81], v[182:185], v[190:193], v[66:81]
	ds_read_b64_tr_b16 v[190:191], v254 offset:49408
	ds_read_b64_tr_b16 v[192:193], v254 offset:53504
	v_sub_f32_e32 v133, v133, v0
	v_exp_f32_e32 v133, v133
	v_add_f32_e32 v130, v132, v130
	s_cmp_le_u32 s47, s44
	s_cbranch_scc0 .Lmy_a_nov1
	s_mov_b32 m0, s54
	s_nop 0
	global_load_lds_dwordx4 v[206:207], off
.Lmy_a_nov1:
	s_waitcnt lgkmcnt(4)
	v_mfma_f32_32x32x16_bf16 v[50:65], v[182:185], v[248:251], v[50:65]
	ds_read_b64_tr_b16 v[248:249], v195 offset:49408
	ds_read_b64_tr_b16 v[250:251], v195 offset:53504
	v_sub_f32_e32 v134, v134, v0
	v_exp_f32_e32 v134, v134
	v_add_f32_e32 v130, v133, v130
	s_waitcnt lgkmcnt(4)
	v_mfma_f32_32x32x16_bf16 v[34:49], v[182:185], v[186:189], v[34:49]
	ds_read_b64_tr_b16 v[186:187], v252 offset:57344
	ds_read_b64_tr_b16 v[188:189], v252 offset:61440
	v_sub_f32_e32 v135, v135, v0
	v_exp_f32_e32 v135, v135
	v_add_f32_e32 v130, v134, v130
	s_waitcnt lgkmcnt(4)
	v_mfma_f32_32x32x16_bf16 v[18:33], v[182:185], v[190:193], v[18:33]
	ds_read_b64_tr_b16 v[190:191], v253 offset:57344
	ds_read_b64_tr_b16 v[192:193], v253 offset:61440
	v_sub_f32_e32 v136, v136, v0
	v_exp_f32_e32 v136, v136
	v_add_f32_e32 v130, v135, v130
	s_waitcnt lgkmcnt(4)
	v_mfma_f32_32x32x16_bf16 v[2:17], v[182:185], v[248:251], v[2:17]
	ds_read_b64_tr_b16 v[182:183], v254 offset:57344
	ds_read_b64_tr_b16 v[184:185], v254 offset:61440
	v_sub_f32_e32 v137, v137, v0
	v_exp_f32_e32 v137, v137
	v_add_f32_e32 v130, v136, v130
	s_waitcnt lgkmcnt(4)
	v_mfma_f32_32x32x16_bf16 v[114:129], v[178:181], v[186:189], v[114:129]
	ds_read_b64_tr_b16 v[248:249], v195 offset:57344
	ds_read_b64_tr_b16 v[250:251], v195 offset:61440
	v_sub_f32_e32 v138, v138, v0
	v_exp_f32_e32 v138, v138
	v_add_f32_e32 v130, v137, v130
	s_waitcnt lgkmcnt(4)
	v_mfma_f32_32x32x16_bf16 v[98:113], v[178:181], v[190:193], v[98:113]
	ds_read_b64_tr_b16 v[190:191], v252 offset:57600
	ds_read_b64_tr_b16 v[192:193], v252 offset:61696
	v_sub_f32_e32 v139, v139, v0
	v_exp_f32_e32 v139, v139
	v_add_f32_e32 v130, v138, v130
	s_cmp_le_u32 s47, s44
	s_cbranch_scc0 .Lmy_a_nov2
	s_mov_b32 m0, s55
	s_nop 0
	global_load_lds_dwordx4 v[204:205], off
.Lmy_a_nov2:
	s_waitcnt lgkmcnt(4)
	v_mfma_f32_32x32x16_bf16 v[82:97], v[178:181], v[182:185], v[82:97]
	ds_read_b64_tr_b16 v[182:183], v253 offset:57600
	ds_read_b64_tr_b16 v[184:185], v253 offset:61696
	v_sub_f32_e32 v140, v140, v0
	v_exp_f32_e32 v140, v140
	v_add_f32_e32 v130, v139, v130
	s_waitcnt lgkmcnt(4)
	v_mfma_f32_32x32x16_bf16 v[66:81], v[178:181], v[248:251], v[66:81]
	ds_read_b64_tr_b16 v[248:249], v254 offset:57600
	ds_read_b64_tr_b16 v[250:251], v254 offset:61696
	v_sub_f32_e32 v141, v141, v0
	v_exp_f32_e32 v141, v141
	v_add_f32_e32 v130, v140, v130
	s_waitcnt lgkmcnt(4)
	v_mfma_f32_32x32x16_bf16 v[50:65], v[178:181], v[190:193], v[50:65]
	ds_read_b64_tr_b16 v[190:191], v195 offset:57600
	ds_read_b64_tr_b16 v[192:193], v195 offset:61696
	v_sub_f32_e32 v142, v142, v0
	v_exp_f32_e32 v142, v142
	v_add_f32_e32 v130, v141, v130
	s_waitcnt lgkmcnt(4)
	v_mfma_f32_32x32x16_bf16 v[34:49], v[178:181], v[182:185], v[34:49]
	v_sub_f32_e32 v143, v143, v0
	v_exp_f32_e32 v143, v143
	v_add_f32_e32 v130, v142, v130
	s_waitcnt lgkmcnt(2)
	v_mfma_f32_32x32x16_bf16 v[18:33], v[178:181], v[248:251], v[18:33]
	v_sub_f32_e32 v144, v144, v0
	v_exp_f32_e32 v144, v144
	v_add_f32_e32 v130, v143, v130
	s_waitcnt lgkmcnt(0)
	v_mfma_f32_32x32x16_bf16 v[2:17], v[178:181], v[190:193], v[2:17]
	v_sub_f32_e32 v145, v145, v0
	v_exp_f32_e32 v145, v145
	v_add_f32_e32 v130, v144, v130
	s_cbranch_vccz .LBB0_295
	ds_write_b32 v226, v247
	ds_read_b128 v[190:193], v227 offset:96
	ds_read_b128 v[186:189], v227 offset:64
	ds_read_b128 v[182:185], v227 offset:32
	ds_read_b128 v[178:181], v227
	s_waitcnt lgkmcnt(3)
	v_pk_mul_f32 v[128:129], v[128:129], v[192:193]
	s_waitcnt lgkmcnt(2)
	v_pk_mul_f32 v[124:125], v[124:125], v[188:189]
	s_waitcnt lgkmcnt(1)
	v_pk_mul_f32 v[120:121], v[120:121], v[184:185]
	s_waitcnt lgkmcnt(0)
	v_pk_mul_f32 v[116:117], v[116:117], v[180:181]
	v_pk_mul_f32 v[126:127], v[126:127], v[190:191]
	v_pk_mul_f32 v[122:123], v[122:123], v[186:187]
	v_pk_mul_f32 v[118:119], v[118:119], v[182:183]
	v_pk_mul_f32 v[114:115], v[114:115], v[178:179]
	v_pk_mul_f32 v[112:113], v[112:113], v[192:193]
	v_pk_mul_f32 v[108:109], v[108:109], v[188:189]
	v_pk_mul_f32 v[104:105], v[104:105], v[184:185]
	v_pk_mul_f32 v[100:101], v[100:101], v[180:181]
	v_pk_mul_f32 v[110:111], v[110:111], v[190:191]
	v_pk_mul_f32 v[106:107], v[106:107], v[186:187]
	v_pk_mul_f32 v[102:103], v[102:103], v[182:183]
	v_pk_mul_f32 v[98:99], v[98:99], v[178:179]
	v_pk_mul_f32 v[96:97], v[96:97], v[192:193]
	v_pk_mul_f32 v[92:93], v[92:93], v[188:189]
	v_pk_mul_f32 v[88:89], v[88:89], v[184:185]
	v_pk_mul_f32 v[84:85], v[84:85], v[180:181]
	v_pk_mul_f32 v[94:95], v[94:95], v[190:191]
	v_pk_mul_f32 v[90:91], v[90:91], v[186:187]
	v_pk_mul_f32 v[86:87], v[86:87], v[182:183]
	v_pk_mul_f32 v[82:83], v[82:83], v[178:179]
	v_pk_mul_f32 v[80:81], v[80:81], v[192:193]
	v_pk_mul_f32 v[76:77], v[76:77], v[188:189]
	v_pk_mul_f32 v[72:73], v[72:73], v[184:185]
	v_pk_mul_f32 v[68:69], v[68:69], v[180:181]
	v_pk_mul_f32 v[78:79], v[78:79], v[190:191]
	v_pk_mul_f32 v[74:75], v[74:75], v[186:187]
	v_pk_mul_f32 v[70:71], v[70:71], v[182:183]
	v_pk_mul_f32 v[66:67], v[66:67], v[178:179]
	v_pk_mul_f32 v[64:65], v[64:65], v[192:193]
	v_pk_mul_f32 v[60:61], v[60:61], v[188:189]
	v_pk_mul_f32 v[56:57], v[56:57], v[184:185]
	v_pk_mul_f32 v[52:53], v[52:53], v[180:181]
	v_pk_mul_f32 v[62:63], v[62:63], v[190:191]
	v_pk_mul_f32 v[58:59], v[58:59], v[186:187]
	v_pk_mul_f32 v[54:55], v[54:55], v[182:183]
	v_pk_mul_f32 v[50:51], v[50:51], v[178:179]
	v_pk_mul_f32 v[48:49], v[48:49], v[192:193]
	v_pk_mul_f32 v[44:45], v[44:45], v[188:189]
	v_pk_mul_f32 v[40:41], v[40:41], v[184:185]
	v_pk_mul_f32 v[36:37], v[36:37], v[180:181]
	v_pk_mul_f32 v[46:47], v[46:47], v[190:191]
	v_pk_mul_f32 v[42:43], v[42:43], v[186:187]
	v_pk_mul_f32 v[38:39], v[38:39], v[182:183]
	v_pk_mul_f32 v[34:35], v[34:35], v[178:179]
	v_pk_mul_f32 v[32:33], v[32:33], v[192:193]
	v_pk_mul_f32 v[28:29], v[28:29], v[188:189]
	v_pk_mul_f32 v[24:25], v[24:25], v[184:185]
	v_pk_mul_f32 v[20:21], v[20:21], v[180:181]
	v_pk_mul_f32 v[30:31], v[30:31], v[190:191]
	v_pk_mul_f32 v[26:27], v[26:27], v[186:187]
	v_pk_mul_f32 v[22:23], v[22:23], v[182:183]
	v_pk_mul_f32 v[18:19], v[18:19], v[178:179]
	v_pk_mul_f32 v[16:17], v[16:17], v[192:193]
	v_pk_mul_f32 v[12:13], v[12:13], v[188:189]
	v_pk_mul_f32 v[8:9], v[8:9], v[184:185]
	v_pk_mul_f32 v[4:5], v[4:5], v[180:181]
	v_pk_mul_f32 v[14:15], v[14:15], v[190:191]
	v_pk_mul_f32 v[10:11], v[10:11], v[186:187]
	v_pk_mul_f32 v[6:7], v[6:7], v[182:183]
	v_pk_mul_f32 v[2:3], v[2:3], v[178:179]

.LBB0_1615:
	v_add_u32_e32 v0, s2, v199
	ds_read_b128 v[130:133], v0
	s_add_i32 s0, s45, -2
	ds_read_b128 v[188:191], v0 offset:1024
	ds_read_b128 v[248:251], v0 offset:2048
	ds_read_b128 v[214:217], v0 offset:3072
	s_waitcnt lgkmcnt(3)
	v_mfma_f32_32x32x16_bf16 v[130:145], v[130:133], v[146:149], 0
	s_waitcnt lgkmcnt(2)
	v_mfma_f32_32x32x16_bf16 v[130:145], v[188:191], v[150:153], v[130:145]
	ds_read_b128 v[188:191], v0 offset:4096
	s_cmp_lt_u32 s45, s42
	s_cbranch_scc0 .Lmy_b_nok1
	s_mov_b32 m0, s52
	s_nop 0
	global_load_lds_dwordx4 v[210:211], off
.Lmy_b_nok1:
	s_waitcnt lgkmcnt(2)
	v_mfma_f32_32x32x16_bf16 v[130:145], v[248:251], v[154:157], v[130:145]
	ds_read_b128 v[248:251], v0 offset:5120
	s_waitcnt lgkmcnt(2)
	v_mfma_f32_32x32x16_bf16 v[130:145], v[214:217], v[158:161], v[130:145]
	ds_read_b128 v[214:217], v0 offset:6144
	s_waitcnt lgkmcnt(2)
	v_mfma_f32_32x32x16_bf16 v[130:145], v[188:191], v[162:165], v[130:145]
	ds_read_b128 v[188:191], v0 offset:7168
	s_cmp_lt_u32 s45, s42
	s_cbranch_scc0 .Lmy_b_nok2
	s_mov_b32 m0, s53
	s_nop 0
	global_load_lds_dwordx4 v[208:209], off
.Lmy_b_nok2:
	s_waitcnt lgkmcnt(2)
	v_mfma_f32_32x32x16_bf16 v[130:145], v[248:251], v[166:169], v[130:145]
	s_waitcnt lgkmcnt(1)
	v_mfma_f32_32x32x16_bf16 v[130:145], v[214:217], v[170:173], v[130:145]
	s_waitcnt lgkmcnt(0)
	v_mfma_f32_32x32x16_bf16 v[130:145], v[188:191], v[174:177], v[130:145]
	s_lshl_b32 s3, s47, 14
	v_add_u32_e32 v252, s3, v224
	v_add_u32_e32 v253, s3, v228
	ds_read_b64_tr_b16 v[190:191], v252 offset:49152
	ds_read_b64_tr_b16 v[192:193], v252 offset:53248
	ds_read_b64_tr_b16 v[248:249], v253 offset:49152
	ds_read_b64_tr_b16 v[250:251], v253 offset:53248
	s_cmp_lt_u32 s0, s41
	s_cbranch_scc1 .LBB0_1617
	v_add_u32_e32 v0, s44, v223
	v_add_u32_e32 v187, 32, v0
	v_cmp_lt_u32_e32 vcc, v187, v201
	s_nop 1
	v_cndmask_b32_e32 v131, v246, v131, vcc
	v_cmp_le_u32_e32 vcc, v187, v201
	v_add_u32_e32 v187, 34, v0
	s_nop 0
	v_cndmask_b32_e32 v130, v246, v130, vcc
	v_cmp_le_u32_e32 vcc, v187, v201
	v_add_u32_e32 v187, 35, v0
	s_nop 0
	v_cndmask_b32_e32 v132, v246, v132, vcc
	v_cmp_le_u32_e32 vcc, v187, v201
	v_add_u32_e32 v187, 40, v0
	s_nop 0
	v_cndmask_b32_e32 v133, v246, v133, vcc
	v_cmp_le_u32_e32 vcc, v187, v201
	v_add_u32_e32 v187, 41, v0
	s_nop 0
	v_cndmask_b32_e32 v134, v246, v134, vcc
	v_cmp_le_u32_e32 vcc, v187, v201
	v_add_u32_e32 v187, 42, v0
	s_nop 0
	v_cndmask_b32_e32 v135, v246, v135, vcc
	v_cmp_le_u32_e32 vcc, v187, v201
	v_add_u32_e32 v187, 43, v0
	s_nop 0
	v_cndmask_b32_e32 v136, v246, v136, vcc
	v_cmp_le_u32_e32 vcc, v187, v201
	v_add_u32_e32 v187, 48, v0
	s_nop 0
	v_cndmask_b32_e32 v137, v246, v137, vcc
	v_cmp_le_u32_e32 vcc, v187, v201
	v_add_u32_e32 v187, 49, v0
	s_nop 0
	v_cndmask_b32_e32 v138, v246, v138, vcc
	v_cmp_le_u32_e32 vcc, v187, v201
	v_add_u32_e32 v187, 50, v0
	s_nop 0
	v_cndmask_b32_e32 v139, v246, v139, vcc
	v_cmp_le_u32_e32 vcc, v187, v201
	v_add_u32_e32 v187, 51, v0
	s_nop 0
	v_cndmask_b32_e32 v140, v246, v140, vcc
	v_cmp_le_u32_e32 vcc, v187, v201
	v_add_u32_e32 v187, 56, v0
	s_nop 0
	v_cndmask_b32_e32 v141, v246, v141, vcc
	v_cmp_le_u32_e32 vcc, v187, v201
	v_add_u32_e32 v187, 57, v0
	s_nop 0
	v_cndmask_b32_e32 v142, v246, v142, vcc
	v_cmp_le_u32_e32 vcc, v187, v201
	v_add_u32_e32 v187, 58, v0
	v_add_u32_e32 v0, 59, v0
	v_cndmask_b32_e32 v143, v246, v143, vcc
	v_cmp_le_u32_e32 vcc, v187, v201
	s_nop 1
	v_cndmask_b32_e32 v144, v246, v144, vcc
	v_cmp_le_u32_e32 vcc, v0, v201
	s_nop 1
	v_cndmask_b32_e32 v145, v246, v145, vcc
.LBB0_1617:
	s_nop 2
	v_max3_f32 v0, v130, v131, v132
	v_max3_f32 v187, v133, v134, v135
	v_max3_f32 v188, v136, v137, v138
	v_max3_f32 v189, v139, v140, v141
	v_max3_f32 v0, v0, v142, v143
	v_max3_f32 v187, v187, v144, v145
	v_max3_f32 v0, v0, v187, v188
	v_max_f32_e32 v0, v0, v189
	v_mov_b32_e32 v187, v0
	s_nop 1
	v_permlane32_swap_b32_e32 v0, v187
	v_max_f32_e32 v0, v0, v187
	v_add_f32_e32 v187, 0x41000000, v186
	v_cmp_gt_f32_e32 vcc, v0, v187
	s_cmp_eq_u64 vcc, 0
	v_max_f32_e32 v0, v186, v0
	s_cselect_b64 s[0:1], -1, 0
	v_cndmask_b32_e64 v0, v0, v186, s[0:1]
	v_sub_f32_e32 v247, v186, v0
	v_exp_f32_e32 v247, v247
	v_add_u32_e32 v254, s3, v229
	ds_read_b64_tr_b16 v[186:187], v254 offset:49152
	ds_read_b64_tr_b16 v[188:189], v254 offset:53248
	s_waitcnt lgkmcnt(4)
	v_mfma_f32_32x32x16_bf16 v[114:129], v[182:185], v[190:193], v[114:129]
	v_add_u32_e32 v195, s3, v230
	ds_read_b64_tr_b16 v[190:191], v195 offset:49152
	ds_read_b64_tr_b16 v[192:193], v195 offset:53248
	v_sub_f32_e32 v130, v130, v0
	v_exp_f32_e32 v1, v130
	s_waitcnt lgkmcnt(4)
	v_mfma_f32_32x32x16_bf16 v[98:113], v[182:185], v[248:251], v[98:113]
	ds_read_b64_tr_b16 v[248:249], v252 offset:49408
	ds_read_b64_tr_b16 v[250:251], v252 offset:53504
	v_sub_f32_e32 v131, v131, v0
	v_exp_f32_e32 v131, v131
	v_add_f32_e32 v130, 0, v1
	s_waitcnt lgkmcnt(4)
	v_mfma_f32_32x32x16_bf16 v[82:97], v[182:185], v[186:189], v[82:97]
	ds_read_b64_tr_b16 v[186:187], v253 offset:49408
	ds_read_b64_tr_b16 v[188:189], v253 offset:53504
	v_sub_f32_e32 v132, v132, v0
	v_exp_f32_e32 v132, v132
	v_add_f32_e32 v130, v131, v130
	s_waitcnt lgkmcnt(4)
	v_mfma_f32_32x32x16_bf16 v[66:81], v[182:185], v[190:193], v[66:81]
	ds_read_b64_tr_b16 v[190:191], v254 offset:49408
	ds_read_b64_tr_b16 v[192:193], v254 offset:53504
	v_sub_f32_e32 v133, v133, v0
	v_exp_f32_e32 v133, v133
	v_add_f32_e32 v130, v132, v130
	s_cmp_le_u32 s45, s42
	s_cbranch_scc0 .Lmy_b_nov1
	s_mov_b32 m0, s54
	s_nop 0
	global_load_lds_dwordx4 v[206:207], off
.Lmy_b_nov1:
	s_waitcnt lgkmcnt(4)
	v_mfma_f32_32x32x16_bf16 v[50:65], v[182:185], v[248:251], v[50:65]
	ds_read_b64_tr_b16 v[248:249], v195 offset:49408
	ds_read_b64_tr_b16 v[250:251], v195 offset:53504
	v_sub_f32_e32 v134, v134, v0
	v_exp_f32_e32 v134, v134
	v_add_f32_e32 v130, v133, v130
	s_waitcnt lgkmcnt(4)
	v_mfma_f32_32x32x16_bf16 v[34:49], v[182:185], v[186:189], v[34:49]
	ds_read_b64_tr_b16 v[186:187], v252 offset:57344
	ds_read_b64_tr_b16 v[188:189], v252 offset:61440
	v_sub_f32_e32 v135, v135, v0
	v_exp_f32_e32 v135, v135
	v_add_f32_e32 v130, v134, v130
	s_waitcnt lgkmcnt(4)
	v_mfma_f32_32x32x16_bf16 v[18:33], v[182:185], v[190:193], v[18:33]
	ds_read_b64_tr_b16 v[190:191], v253 offset:57344
	ds_read_b64_tr_b16 v[192:193], v253 offset:61440
	v_sub_f32_e32 v136, v136, v0
	v_exp_f32_e32 v136, v136
	v_add_f32_e32 v130, v135, v130
	s_waitcnt lgkmcnt(4)
	v_mfma_f32_32x32x16_bf16 v[2:17], v[182:185], v[248:251], v[2:17]
	ds_read_b64_tr_b16 v[182:183], v254 offset:57344
	ds_read_b64_tr_b16 v[184:185], v254 offset:61440
	v_sub_f32_e32 v137, v137, v0
	v_exp_f32_e32 v137, v137
	v_add_f32_e32 v130, v136, v130
	s_waitcnt lgkmcnt(4)
	v_mfma_f32_32x32x16_bf16 v[114:129], v[178:181], v[186:189], v[114:129]
	ds_read_b64_tr_b16 v[248:249], v195 offset:57344
	ds_read_b64_tr_b16 v[250:251], v195 offset:61440
	v_sub_f32_e32 v138, v138, v0
	v_exp_f32_e32 v138, v138
	v_add_f32_e32 v130, v137, v130
	s_waitcnt lgkmcnt(4)
	v_mfma_f32_32x32x16_bf16 v[98:113], v[178:181], v[190:193], v[98:113]
	ds_read_b64_tr_b16 v[190:191], v252 offset:57600
	ds_read_b64_tr_b16 v[192:193], v252 offset:61696
	v_sub_f32_e32 v139, v139, v0
	v_exp_f32_e32 v139, v139
	v_add_f32_e32 v130, v138, v130
	s_cmp_le_u32 s45, s42
	s_cbranch_scc0 .Lmy_b_nov2
	s_mov_b32 m0, s55
	s_nop 0
	global_load_lds_dwordx4 v[204:205], off
